# attention: first four V-fragment LDS reads of each PV block issued before the wave's LDS-DMA issue block
# speedup vs baseline: 1.0001x; 1.0001x over previous
; #define LAS __attribute__((address_space(3)))
; #define AT_VLD(dst, db_) { _Pragma("unroll") for (int s2 = 0; s2 < 2; ++s2) { const LAS bf16* vp = Vs + ((db_) * 16 + lc) * 72 + 32 * s2 + 4 * g4; \
;                     const u32x2 v0 = *(const LAS u32x2*)vp, v1 = *(const LAS u32x2*)(vp + 16); const u32x4 vw = (u32x4){v0.x, v0.y, v1.x, v1.y}; dst[s2] = __builtin_bit_cast(bf16x8, vw); } }
; DI void u_attn2(Frame& F, int h, int qb, int sp, int ntile) {
;     ...
;     for (int t = 0; t < ntile; ++t) {
;         const int kt = kt0 + t;
;         __syncthreads();
; #pragma unroll
;         for (int i = 0; i < 3; ++i) { const int p = tid + 512 * i, r = p / 24, cc = p - r * 24; *(LAS u32x4*)(Ks + r * 200 + cc * 8) = kreg[i]; }
; #pragma unroll
;         for (int i = 0; i < 2; ++i) { const int p = tid + 512 * i, r = p >> 3, cc = p & 7; *(LAS u32x4*)(Vs + r * 72 + cc * 8) = vreg[i]; }
;         __syncthreads();
;         if (t + 1 < ntile) AT_LOAD(kt + 1)
;     ...
;             {
;                 bf16x8 vfr[2][2];
;     ...
;                 AT_VLD(vfr[0], 0)
.LBB0_2237:
	s_barrier
	s_add_i32 s39, s47, 0xb800
	s_cmp_eq_u32 s39, 0x22800
	s_cselect_b32 s39, 0, s39
	s_add_i32 s38, s39, 0xb800
	s_cmp_eq_u32 s38, 0x22800
	s_cselect_b32 s38, 0, s38
	v_add_u32_e32 v112, s47, v187
	v_add_u32_e32 v110, s38, v111
	v_mov_b32_e32 v234, 0x42800000
	s_cmp_lt_i32 s24, 4
	s_cbranch_scc0 .Latt_gB
	ds_read_b128 v[146:149], v110 offset:26624
	ds_read_b128 v[244:247], v110 offset:26688
	ds_read_b128 v[220:223], v110 offset:29184
	ds_read_b128 v[224:227], v110 offset:29248
	s_lshl_b32 vcc_lo, s24, 10
	s_add_i32 vcc_lo, vcc_lo, s11
	s_add_i32 vcc_hi, s46, 2
	s_cmp_lt_i32 vcc_hi, s45
	s_cbranch_scc0 .Latt_vonly_A
	s_add_i32 m0, s38, vcc_lo
	s_nop 0
	global_load_lds_dwordx4 v122, s[48:49]
	s_add_i32 m0, m0, 0x2000
	s_nop 0
	global_load_lds_dwordx4 v123, s[48:49]
	s_add_i32 m0, m0, 0x2000
	s_nop 0
	global_load_lds_dwordx4 v124, s[48:49]
	s_branch .Latt_vjobs_A

; #define MFMA16(a, b, c) __builtin_amdgcn_mfma_f32_16x16x32_bf16((a), (b), (c), 0, 0, 0)
; #define AT_VLD(dst, db_) { _Pragma("unroll") for (int s2 = 0; s2 < 2; ++s2) { const LAS bf16* vp = Vs + ((db_) * 16 + lc) * 72 + 32 * s2 + 4 * g4; \
;                     const u32x2 v0 = *(const LAS u32x2*)vp, v1 = *(const LAS u32x2*)(vp + 16); const u32x4 vw = (u32x4){v0.x, v0.y, v1.x, v1.y}; dst[s2] = __builtin_bit_cast(bf16x8, vw); } }
; DI void u_attn2(Frame& F, int h, int qb, int sp, int ntile) {
;     ...
;             {
;                 bf16x8 vfr[2][2];
;     ...
;                 AT_VLD(vfr[0], 0)
; #pragma unroll
;                 for (int db = 0; db < 8; ++db) {
;                     if (db < 7) AT_VLD(vfr[(db + 1) & 1], db + 1)
; #pragma unroll
;                     for (int s2 = 0; s2 < 2; ++s2)
; #pragma unroll
;                         for (int qq = 0; qq < 2; ++qq) o[db][qq] = MFMA16(vfr[db & 1][s2], pf[qq][s2], o[db][qq]);
;                 }
.Latt_noload_A:
	s_cmp_eq_u32 s46, 0
	s_cbranch_scc1 .Latt_A_qk
	v_add3_u32 v18, s46, v181, -1
	v_cmp_le_i32_e32 vcc, v18, v180
	s_cbranch_vccz .Latt_A_qk
	s_waitcnt lgkmcnt(3)
	v_mfma_f32_16x16x32_bf16 v[134:137], v[146:149], v[198:201], v[134:137]
	v_mfma_f32_16x16x32_bf16 v[118:121], v[146:149], v[210:213], v[118:121]
	ds_read_b128 v[146:149], v110 offset:31744
	s_waitcnt lgkmcnt(3)
	v_mfma_f32_16x16x32_bf16 v[134:137], v[244:247], v[192:195], v[134:137]
	v_mfma_f32_16x16x32_bf16 v[118:121], v[244:247], v[142:145], v[118:121]
	ds_read_b128 v[244:247], v110 offset:31808
	s_waitcnt lgkmcnt(3)
	v_mfma_f32_16x16x32_bf16 v[106:109], v[220:223], v[198:201], v[106:109]
	v_mfma_f32_16x16x32_bf16 v[102:105], v[220:223], v[210:213], v[102:105]
	ds_read_b128 v[220:223], v110 offset:34304
	s_waitcnt lgkmcnt(3)
	v_mfma_f32_16x16x32_bf16 v[106:109], v[224:227], v[192:195], v[106:109]
	v_mfma_f32_16x16x32_bf16 v[102:105], v[224:227], v[142:145], v[102:105]
	ds_read_b128 v[224:227], v110 offset:34368
	s_waitcnt lgkmcnt(3)
	v_mfma_f32_16x16x32_bf16 v[98:101], v[146:149], v[198:201], v[98:101]
	v_mfma_f32_16x16x32_bf16 v[94:97], v[146:149], v[210:213], v[94:97]
	ds_read_b128 v[146:149], v110 offset:36864
	s_waitcnt lgkmcnt(3)
	v_mfma_f32_16x16x32_bf16 v[98:101], v[244:247], v[192:195], v[98:101]
	v_mfma_f32_16x16x32_bf16 v[94:97], v[244:247], v[142:145], v[94:97]
	ds_read_b128 v[244:247], v110 offset:36928
	s_waitcnt lgkmcnt(3)
	v_mfma_f32_16x16x32_bf16 v[90:93], v[220:223], v[198:201], v[90:93]
	v_mfma_f32_16x16x32_bf16 v[86:89], v[220:223], v[210:213], v[86:89]
	ds_read_b128 v[220:223], v110 offset:39424
	s_waitcnt lgkmcnt(3)
	v_mfma_f32_16x16x32_bf16 v[90:93], v[224:227], v[192:195], v[90:93]
	v_mfma_f32_16x16x32_bf16 v[86:89], v[224:227], v[142:145], v[86:89]
	ds_read_b128 v[224:227], v110 offset:39488
	s_waitcnt lgkmcnt(3)
	v_mfma_f32_16x16x32_bf16 v[82:85], v[146:149], v[198:201], v[82:85]
	v_mfma_f32_16x16x32_bf16 v[78:81], v[146:149], v[210:213], v[78:81]
	ds_read_b128 v[146:149], v110 offset:41984
	s_waitcnt lgkmcnt(3)
	v_mfma_f32_16x16x32_bf16 v[82:85], v[244:247], v[192:195], v[82:85]
	v_mfma_f32_16x16x32_bf16 v[78:81], v[244:247], v[142:145], v[78:81]
	ds_read_b128 v[244:247], v110 offset:42048
	s_waitcnt lgkmcnt(3)
	v_mfma_f32_16x16x32_bf16 v[70:73], v[220:223], v[198:201], v[70:73]
	v_mfma_f32_16x16x32_bf16 v[74:77], v[220:223], v[210:213], v[74:77]
	ds_read_b128 v[220:223], v110 offset:44544
	s_waitcnt lgkmcnt(3)
	v_mfma_f32_16x16x32_bf16 v[70:73], v[224:227], v[192:195], v[70:73]
	v_mfma_f32_16x16x32_bf16 v[74:77], v[224:227], v[142:145], v[74:77]
	ds_read_b128 v[224:227], v110 offset:44608
	s_waitcnt lgkmcnt(3)
	v_mfma_f32_16x16x32_bf16 v[66:69], v[146:149], v[198:201], v[66:69]
	v_mfma_f32_16x16x32_bf16 v[58:61], v[146:149], v[210:213], v[58:61]
	s_waitcnt lgkmcnt(2)
	v_mfma_f32_16x16x32_bf16 v[66:69], v[244:247], v[192:195], v[66:69]
	v_mfma_f32_16x16x32_bf16 v[58:61], v[244:247], v[142:145], v[58:61]
	s_waitcnt lgkmcnt(1)
	v_mfma_f32_16x16x32_bf16 v[54:57], v[220:223], v[198:201], v[54:57]
	v_mfma_f32_16x16x32_bf16 v[62:65], v[220:223], v[210:213], v[62:65]
	s_waitcnt lgkmcnt(0)
	v_mfma_f32_16x16x32_bf16 v[54:57], v[224:227], v[192:195], v[54:57]
	v_mfma_f32_16x16x32_bf16 v[62:65], v[224:227], v[142:145], v[62:65]

; DI unsigned pk2(float lo, float hi) { const f32x2 v = {lo, hi}; const bf16x2_t b = __builtin_convertvector(v, bf16x2_t); return __builtin_bit_cast(unsigned, b); }
; DI float xr16_sum(float x) { float a = x, b = x; XR_SWAP("v_permlane16_swap_b32", a, b); return a + b; }
; DI float xr32_sum(float x) { float a = x, b = x; XR_SWAP("v_permlane32_swap_b32", a, b); return a + b; }
; #define AT_VLD(dst, db_) { _Pragma("unroll") for (int s2 = 0; s2 < 2; ++s2) { const LAS bf16* vp = Vs + ((db_) * 16 + lc) * 72 + 32 * s2 + 4 * g4; \
;                     const u32x2 v0 = *(const LAS u32x2*)vp, v1 = *(const LAS u32x2*)(vp + 16); const u32x4 vw = (u32x4){v0.x, v0.y, v1.x, v1.y}; dst[s2] = __builtin_bit_cast(bf16x8, vw); } }
; DI void u_attn2(Frame& F, int h, int qb, int sp, int ntile) {
;     ...
;                 float ps = 0.f; float p[16];
; #pragma unroll
;                 for (int kb = 0; kb < 4; ++kb)
; #pragma unroll
;                     for (int r = 0; r < 4; ++r) { p[kb * 4 + r] = __builtin_amdgcn_exp2f(s[kb][qq][r] - mn); ps += p[kb * 4 + r]; }
;                 ps = xr32_sum(xr16_sum(ps));
;                 lrun[qq] = lrun[qq] * alpha + ps;
; if (__builtin_amdgcn_ballot_w64(alpha != 1.0f) != 0ull) {
; #pragma unroll
;                     for (int db = 0; db < 8; ++db) o[db][qq] = o[db][qq] * alpha; }
; #pragma unroll
;                 for (int s2 = 0; s2 < 2; ++s2) { u32x4 pw; pw.x = pk2(p[8 * s2], p[8 * s2 + 1]); pw.y = pk2(p[8 * s2 + 2], p[8 * s2 + 3]); pw.z = pk2(p[8 * s2 + 4], p[8 * s2 + 5]); pw.w = pk2(p[8 * s2 + 6], p[8 * s2 + 7]); pf[qq][s2] = __builtin_bit_cast(bf16x8, pw); }
;             }
;             {
;                 bf16x8 vfr[2][2];
;     ...
;                 AT_VLD(vfr[0], 0)
.Latt_r1_B:
	v_exp_f32_e32 v218, v218
	v_exp_f32_e32 v219, v219
	v_exp_f32_e32 v220, v220
	v_exp_f32_e32 v221, v221
	v_exp_f32_e32 v214, v214
	v_exp_f32_e32 v215, v215
	v_exp_f32_e32 v216, v216
	v_exp_f32_e32 v217, v217
	v_exp_f32_e32 v222, v222
	v_exp_f32_e32 v223, v223
	v_exp_f32_e32 v224, v224
	v_exp_f32_e32 v225, v225
	v_exp_f32_e32 v154, v154
	v_exp_f32_e32 v155, v155
	v_exp_f32_e32 v156, v156
	v_exp_f32_e32 v157, v157
	v_exp_f32_e32 v150, v150
	v_exp_f32_e32 v151, v151
	v_exp_f32_e32 v152, v152
	v_exp_f32_e32 v153, v153
	v_exp_f32_e32 v146, v146
	v_exp_f32_e32 v147, v147
	v_exp_f32_e32 v148, v148
	v_exp_f32_e32 v149, v149
	v_exp_f32_e32 v142, v142
	v_exp_f32_e32 v143, v143
	v_exp_f32_e32 v144, v144
	v_exp_f32_e32 v145, v145
	v_exp_f32_e32 v138, v138
	v_exp_f32_e32 v139, v139
	v_exp_f32_e32 v140, v140
	v_exp_f32_e32 v141, v141
	v_add_f32_e32 v198, v218, v219
	v_add_f32_e32 v199, v220, v221
	v_add_f32_e32 v200, v214, v215
	v_add_f32_e32 v201, v216, v217
	v_add_f32_e32 v210, v150, v151
	v_add_f32_e32 v211, v152, v153
	v_add_f32_e32 v212, v146, v147
	v_add_f32_e32 v213, v148, v149
	v_add_f32_e32 v198, v198, v222
	v_add_f32_e32 v199, v199, v223
	v_add_f32_e32 v200, v200, v224
	v_add_f32_e32 v201, v201, v225
	v_add_f32_e32 v210, v210, v142
	v_add_f32_e32 v211, v211, v143
	v_add_f32_e32 v212, v212, v144
	v_add_f32_e32 v213, v213, v145
	v_add_f32_e32 v198, v198, v154
	v_add_f32_e32 v199, v199, v155
	v_add_f32_e32 v200, v200, v156
	v_add_f32_e32 v201, v201, v157
	v_add_f32_e32 v210, v210, v138
	v_add_f32_e32 v211, v211, v139
	v_add_f32_e32 v212, v212, v140
	v_add_f32_e32 v213, v213, v141
	v_add_f32_e32 v198, v198, v199
	v_add_f32_e32 v200, v200, v201
	v_add_f32_e32 v210, v210, v211
	v_add_f32_e32 v212, v212, v213
	v_add_f32_e32 v198, v198, v200
	v_add_f32_e32 v210, v210, v212
	v_add_f32_e32 v165, v165, v198
	v_add_f32_e32 v163, v163, v210
	v_cvt_pk_bf16_f32 v198, v218, v219
	v_cvt_pk_bf16_f32 v199, v220, v221
	v_cvt_pk_bf16_f32 v200, v214, v215
	v_cvt_pk_bf16_f32 v201, v216, v217
	v_cvt_pk_bf16_f32 v192, v222, v223
	v_cvt_pk_bf16_f32 v193, v224, v225
	v_cvt_pk_bf16_f32 v194, v154, v155
	v_cvt_pk_bf16_f32 v195, v156, v157
	v_cvt_pk_bf16_f32 v210, v150, v151
	v_cvt_pk_bf16_f32 v211, v152, v153
	v_cvt_pk_bf16_f32 v212, v146, v147
	v_cvt_pk_bf16_f32 v213, v148, v149
	v_cvt_pk_bf16_f32 v142, v142, v143
	v_cvt_pk_bf16_f32 v143, v144, v145
	v_cvt_pk_bf16_f32 v144, v138, v139
	v_cvt_pk_bf16_f32 v145, v140, v141
	ds_read_b128 v[146:149], v110 offset:26624
	ds_read_b128 v[244:247], v110 offset:26688
	ds_read_b128 v[220:223], v110 offset:29184
	ds_read_b128 v[224:227], v110 offset:29248
